# sample cross-attention V phase: second 16 V rows requested after the first 16 are consumed (16 instead of up to 32 cache rows in flight per wave)
# speedup vs baseline: 1.0035x; 1.0035x over previous
.LBB11_2225:
	s_add_u32 s0, s58, s90
	s_addc_u32 s1, s59, s91
	s_lshl_b32 s10, s68, 2
	s_add_u32 s0, s0, s10
	s_addc_u32 s1, s1, 0
	v_lshl_add_u64 v[66:67], v[100:101], 2, s[0:1]
	v_readlane_b32 s0, v243, 2
	v_readlane_b32 s1, v243, 3
	v_mov_b32_e32 v105, s84
	s_waitcnt lgkmcnt(0)
	v_lshl_add_u64 v[2:3], v[66:67], 0, s[0:1]
	v_readlane_b32 s0, v244, 4
	v_readlane_b32 s1, v244, 5
	s_nop 1
	v_lshl_add_u64 v[4:5], v[66:67], 0, s[0:1]
	v_readlane_b32 s0, v244, 6
	v_readlane_b32 s1, v244, 7
	global_load_dwordx4 v[62:65], v[2:3], off nt
	global_load_dwordx4 v[42:45], v[4:5], off nt
	v_lshl_add_u64 v[2:3], v[66:67], 0, s[0:1]
	v_readlane_b32 s0, v244, 8
	v_readlane_b32 s1, v244, 9
	s_nop 1
	v_lshl_add_u64 v[4:5], v[66:67], 0, s[0:1]
	v_readlane_b32 s0, v244, 10
	v_readlane_b32 s1, v244, 11
	global_load_dwordx4 v[58:61], v[2:3], off nt
	global_load_dwordx4 v[34:37], v[4:5], off nt
	v_lshl_add_u64 v[2:3], v[66:67], 0, s[0:1]
	v_readlane_b32 s0, v244, 12
	v_readlane_b32 s1, v244, 13
	s_nop 1
	v_lshl_add_u64 v[4:5], v[66:67], 0, s[0:1]
	v_readlane_b32 s0, v244, 14
	v_readlane_b32 s1, v244, 15
	global_load_dwordx4 v[54:57], v[2:3], off nt
	global_load_dwordx4 v[26:29], v[4:5], off nt
	v_lshl_add_u64 v[2:3], v[66:67], 0, s[0:1]
	v_readlane_b32 s0, v244, 16
	v_readlane_b32 s1, v244, 17
	s_nop 1
	v_lshl_add_u64 v[4:5], v[66:67], 0, s[0:1]
	v_readlane_b32 s0, v244, 18
	v_readlane_b32 s1, v244, 19
	global_load_dwordx4 v[50:53], v[2:3], off nt
	global_load_dwordx4 v[22:25], v[4:5], off nt
	v_lshl_add_u64 v[2:3], v[66:67], 0, s[0:1]
	v_readlane_b32 s0, v244, 20
	v_readlane_b32 s1, v244, 21
	s_nop 1
	v_lshl_add_u64 v[4:5], v[66:67], 0, s[0:1]
	v_readlane_b32 s0, v244, 22
	v_readlane_b32 s1, v244, 23
	global_load_dwordx4 v[46:49], v[2:3], off nt
	global_load_dwordx4 v[18:21], v[4:5], off nt
	v_lshl_add_u64 v[2:3], v[66:67], 0, s[0:1]
	v_readlane_b32 s0, v244, 24
	v_readlane_b32 s1, v244, 25
	s_nop 1
	v_lshl_add_u64 v[4:5], v[66:67], 0, s[0:1]
	v_readlane_b32 s0, v244, 26
	v_readlane_b32 s1, v244, 27
	global_load_dwordx4 v[38:41], v[2:3], off nt
	global_load_dwordx4 v[14:17], v[4:5], off nt
	v_lshl_add_u64 v[2:3], v[66:67], 0, s[0:1]
	v_readlane_b32 s0, v244, 28
	v_readlane_b32 s1, v244, 29
	s_nop 1
	v_lshl_add_u64 v[4:5], v[66:67], 0, s[0:1]
	v_readlane_b32 s0, v244, 30
	v_readlane_b32 s1, v244, 31
	global_load_dwordx4 v[30:33], v[2:3], off nt
	global_load_dwordx4 v[10:13], v[4:5], off nt
	v_lshl_add_u64 v[2:3], v[66:67], 0, s[0:1]
	v_readlane_b32 s0, v244, 32
	v_readlane_b32 s1, v244, 33
	s_nop 1
	v_lshl_add_u64 v[4:5], v[66:67], 0, s[0:1]
	global_load_dwordx4 v[6:9], v[2:3], off nt
	s_nop 0
	global_load_dwordx4 v[2:5], v[4:5], off nt
	s_waitcnt lgkmcnt(0)
	s_barrier
	ds_read2st64_b32 v[68:69], v0 offset1:1
	ds_read2st64_b32 v[70:71], v0 offset0:2 offset1:3
	s_waitcnt lgkmcnt(1)
	v_max3_f32 v72, v68, s72, v69
	s_waitcnt lgkmcnt(0)
	v_max3_f32 v72, v72, v70, v71
	ds_bpermute_b32 v73, v200, v72
	s_waitcnt lgkmcnt(0)
	v_max_f32_e32 v73, v73, v73
	v_max_f32_e32 v72, v72, v73
	ds_bpermute_b32 v73, v201, v72
	s_waitcnt lgkmcnt(0)
	v_max_f32_e32 v73, v73, v73
	v_max_f32_e32 v72, v72, v73
	ds_bpermute_b32 v73, v202, v72
	s_waitcnt lgkmcnt(0)
	v_max_f32_e32 v73, v73, v73
	v_max_f32_e32 v72, v72, v73
	ds_bpermute_b32 v73, v203, v72
	s_waitcnt lgkmcnt(0)
	v_max_f32_e32 v73, v73, v73
	v_max_f32_e32 v72, v72, v73
	ds_bpermute_b32 v73, v204, v72
	s_waitcnt lgkmcnt(0)
	v_max_f32_e32 v73, v73, v73
	v_max_f32_e32 v72, v72, v73
	ds_bpermute_b32 v73, v205, v72
	s_waitcnt lgkmcnt(0)
	v_max_f32_e32 v73, v73, v73
	v_max_f32_e32 v104, v72, v73
	v_sub_f32_e32 v68, v68, v104
	v_mul_f32_e32 v68, 0x3fb8aa3b, v68
	v_sub_f32_e32 v69, v69, v104
	v_exp_f32_e32 v68, v68
	v_mul_f32_e32 v69, 0x3fb8aa3b, v69
	v_sub_f32_e32 v70, v70, v104
	v_exp_f32_e32 v69, v69
	v_mul_f32_e32 v70, 0x3fb8aa3b, v70
	v_sub_f32_e32 v71, v71, v104
	v_exp_f32_e32 v70, v70
	v_mul_f32_e32 v71, 0x3fb8aa3b, v71
	v_exp_f32_e32 v71, v71
	v_add_f32_e32 v68, 0, v68
	v_add_f32_e32 v68, v69, v68
	v_add_f32_e32 v68, v70, v68
	v_add_f32_e32 v68, v71, v68
	ds_bpermute_b32 v69, v200, v68
	s_waitcnt lgkmcnt(0)
	v_add_f32_e32 v68, v68, v69
	ds_bpermute_b32 v69, v201, v68
	s_waitcnt lgkmcnt(0)
	v_add_f32_e32 v68, v68, v69
	ds_bpermute_b32 v69, v202, v68
	s_waitcnt lgkmcnt(0)
	v_add_f32_e32 v68, v68, v69
	ds_bpermute_b32 v69, v203, v68
	s_waitcnt lgkmcnt(0)
	v_add_f32_e32 v76, v68, v69
	ds_bpermute_b32 v77, v204, v76
	ds_read_b128 v[68:71], v105
	ds_read_b128 v[72:75], v105 offset:16
	s_waitcnt lgkmcnt(2)
	v_add_f32_e32 v84, v76, v77
	ds_bpermute_b32 v85, v205, v84
	s_waitcnt lgkmcnt(2)
	v_sub_f32_e32 v68, v68, v104
	v_mul_f32_e32 v68, 0x3fb8aa3b, v68
	v_exp_f32_e32 v68, v68
	ds_read_b128 v[76:79], v105 offset:32
	ds_read_b128 v[80:83], v105 offset:48
	s_waitcnt lgkmcnt(2)
	v_add_f32_e32 v84, v84, v85
	v_div_scale_f32 v85, s[0:1], v84, v84, 1.0
	v_rcp_f32_e32 v86, v85
	v_div_scale_f32 v87, vcc, 1.0, v84, 1.0
	v_fma_f32 v88, -v85, v86, 1.0
	v_fmac_f32_e32 v86, v88, v86
	v_mul_f32_e32 v88, v87, v86
	v_fma_f32 v89, -v85, v88, v87
	v_fmac_f32_e32 v88, v89, v86
	v_fma_f32 v85, -v85, v88, v87
	v_div_fmas_f32 v85, v85, v86, v88
	v_div_fixup_f32 v139, v85, v84, 1.0
	v_mul_f32_e32 v138, v68, v139
	v_sub_f32_e32 v68, v69, v104
	v_sub_f32_e32 v69, v70, v104
	v_mul_f32_e32 v68, 0x3fb8aa3b, v68
	v_mul_f32_e32 v69, 0x3fb8aa3b, v69
	v_sub_f32_e32 v70, v71, v104
	v_exp_f32_e32 v68, v68
	v_exp_f32_e32 v69, v69
	v_mul_f32_e32 v70, 0x3fb8aa3b, v70
	v_exp_f32_e32 v70, v70
	v_sub_f32_e32 v71, v72, v104
	v_mul_f32_e32 v71, 0x3fb8aa3b, v71
	v_mul_f32_e32 v140, v68, v139
	v_mul_f32_e32 v142, v69, v139
	v_sub_f32_e32 v68, v73, v104
	v_sub_f32_e32 v69, v74, v104
	v_exp_f32_e32 v71, v71
	v_mul_f32_e32 v144, v70, v139
	v_mul_f32_e32 v68, 0x3fb8aa3b, v68
	v_mul_f32_e32 v69, 0x3fb8aa3b, v69
	v_sub_f32_e32 v70, v75, v104
	v_exp_f32_e32 v68, v68
	v_exp_f32_e32 v69, v69
	v_mul_f32_e32 v70, 0x3fb8aa3b, v70
	v_exp_f32_e32 v70, v70
	v_mul_f32_e32 v146, v71, v139
	s_waitcnt lgkmcnt(1)
	v_sub_f32_e32 v71, v76, v104
	v_mul_f32_e32 v71, 0x3fb8aa3b, v71
	v_mul_f32_e32 v148, v68, v139
	v_mul_f32_e32 v150, v139, v69
	v_sub_f32_e32 v68, v77, v104
	v_sub_f32_e32 v69, v78, v104
	v_exp_f32_e32 v71, v71
	v_mul_f32_e32 v152, v139, v70
	v_mul_f32_e32 v68, 0x3fb8aa3b, v68
	v_mul_f32_e32 v69, 0x3fb8aa3b, v69
	v_sub_f32_e32 v70, v79, v104
	v_exp_f32_e32 v68, v68
	v_exp_f32_e32 v69, v69
	v_mul_f32_e32 v70, 0x3fb8aa3b, v70
	v_exp_f32_e32 v70, v70
	v_mul_f32_e32 v154, v139, v71
	s_waitcnt lgkmcnt(0)
	v_sub_f32_e32 v71, v80, v104
	v_mul_f32_e32 v71, 0x3fb8aa3b, v71
	v_mul_f32_e32 v156, v139, v68
	v_mul_f32_e32 v158, v139, v69
	v_exp_f32_e32 v71, v71
	v_mul_f32_e32 v160, v139, v70
	v_sub_f32_e32 v70, v81, v104
	v_mul_f32_e32 v68, 0x3fb8aa3b, v70
	v_exp_f32_e32 v70, v68
	v_sub_f32_e32 v68, v82, v104
	v_mul_f32_e32 v68, 0x3fb8aa3b, v68
	v_mul_f32_e32 v162, v139, v71
	v_exp_f32_e32 v71, v68
	v_sub_f32_e32 v68, v83, v104
	v_mul_f32_e32 v72, 0x3fb8aa3b, v68
	v_mul_f32_e32 v164, v139, v70
	v_mul_f32_e32 v166, v139, v71
	v_exp_f32_e32 v72, v72
	s_waitcnt vmcnt(15)
	v_pk_fma_f32 v[62:63], v[62:63], v[138:139], 0 op_sel_hi:[1,0,0]
	v_mul_f32_e32 v168, v139, v72
	v_pk_fma_f32 v[64:65], v[64:65], v[138:139], 0 op_sel_hi:[1,0,0]
	s_waitcnt vmcnt(14)
	v_pk_fma_f32 v[42:43], v[42:43], v[140:141], v[62:63] op_sel_hi:[1,0,1]
	v_pk_fma_f32 v[44:45], v[44:45], v[140:141], v[64:65] op_sel_hi:[1,0,1]
	s_waitcnt vmcnt(13)
	v_pk_fma_f32 v[42:43], v[58:59], v[142:143], v[42:43] op_sel_hi:[1,0,1]
	v_pk_fma_f32 v[44:45], v[60:61], v[142:143], v[44:45] op_sel_hi:[1,0,1]
	s_waitcnt vmcnt(12)
	v_pk_fma_f32 v[34:35], v[34:35], v[144:145], v[42:43] op_sel_hi:[1,0,1]
	v_pk_fma_f32 v[36:37], v[36:37], v[144:145], v[44:45] op_sel_hi:[1,0,1]
	s_waitcnt vmcnt(11)
	v_pk_fma_f32 v[34:35], v[54:55], v[146:147], v[34:35] op_sel_hi:[1,0,1]
	v_pk_fma_f32 v[36:37], v[56:57], v[146:147], v[36:37] op_sel_hi:[1,0,1]
	s_waitcnt vmcnt(10)
	v_pk_fma_f32 v[26:27], v[26:27], v[148:149], v[34:35] op_sel_hi:[1,0,1]
	v_pk_fma_f32 v[28:29], v[28:29], v[148:149], v[36:37] op_sel_hi:[1,0,1]
	s_waitcnt vmcnt(9)
	v_pk_fma_f32 v[26:27], v[50:51], v[150:151], v[26:27] op_sel_hi:[1,0,1]
	v_pk_fma_f32 v[28:29], v[52:53], v[150:151], v[28:29] op_sel_hi:[1,0,1]
	s_waitcnt vmcnt(8)
	v_pk_fma_f32 v[22:23], v[22:23], v[152:153], v[26:27] op_sel_hi:[1,0,1]
	v_pk_fma_f32 v[24:25], v[24:25], v[152:153], v[28:29] op_sel_hi:[1,0,1]
	s_waitcnt vmcnt(7)
	v_pk_fma_f32 v[22:23], v[46:47], v[154:155], v[22:23] op_sel_hi:[1,0,1]
	v_pk_fma_f32 v[24:25], v[48:49], v[154:155], v[24:25] op_sel_hi:[1,0,1]
	s_waitcnt vmcnt(6)
	v_pk_fma_f32 v[18:19], v[18:19], v[156:157], v[22:23] op_sel_hi:[1,0,1]
	s_nop 0
	v_pk_fma_f32 v[20:21], v[20:21], v[156:157], v[24:25] op_sel_hi:[1,0,1]
	s_waitcnt vmcnt(5)
	v_pk_fma_f32 v[18:19], v[38:39], v[158:159], v[18:19] op_sel_hi:[1,0,1]
	v_pk_fma_f32 v[20:21], v[40:41], v[158:159], v[20:21] op_sel_hi:[1,0,1]
	s_waitcnt vmcnt(4)
	v_pk_fma_f32 v[14:15], v[14:15], v[160:161], v[18:19] op_sel_hi:[1,0,1]
	v_pk_fma_f32 v[16:17], v[16:17], v[160:161], v[20:21] op_sel_hi:[1,0,1]
	s_waitcnt vmcnt(3)
	v_pk_fma_f32 v[18:19], v[30:31], v[162:163], v[14:15] op_sel_hi:[1,0,1]
	v_pk_fma_f32 v[20:21], v[32:33], v[162:163], v[16:17] op_sel_hi:[1,0,1]
	ds_read_b128 v[14:17], v105 offset:64
	s_waitcnt vmcnt(2)
	v_pk_fma_f32 v[10:11], v[10:11], v[164:165], v[18:19] op_sel_hi:[1,0,1]
	v_pk_fma_f32 v[20:21], v[12:13], v[164:165], v[20:21] op_sel_hi:[1,0,1]
	s_waitcnt vmcnt(1)
	v_pk_fma_f32 v[6:7], v[6:7], v[166:167], v[10:11] op_sel_hi:[1,0,1]
	ds_read_b128 v[10:13], v105 offset:80
	s_waitcnt lgkmcnt(1)
	v_sub_f32_e32 v14, v14, v104
	v_mul_f32_e32 v14, 0x3fb8aa3b, v14
	v_exp_f32_e32 v14, v14
	v_pk_fma_f32 v[8:9], v[8:9], v[166:167], v[20:21] op_sel_hi:[1,0,1]
	s_waitcnt vmcnt(0)
	v_pk_fma_f32 v[2:3], v[2:3], v[168:169], v[6:7] op_sel_hi:[1,0,1]
	v_pk_fma_f32 v[4:5], v[4:5], v[168:169], v[8:9] op_sel_hi:[1,0,1]
	v_mul_f32_e32 v6, v139, v14
	v_readlane_b32 s0, v244, 34
	v_readlane_b32 s1, v244, 35
	s_nop 1
	v_lshl_add_u64 v[68:69], v[66:67], 0, s[0:1]
	global_load_dwordx4 v[106:109], v[68:69], off nt
	v_readlane_b32 s0, v244, 36
	v_readlane_b32 s1, v244, 37
	s_nop 1
	v_lshl_add_u64 v[68:69], v[66:67], 0, s[0:1]
	v_readlane_b32 s0, v244, 38
	v_readlane_b32 s1, v244, 39
	global_load_dwordx4 v[110:113], v[68:69], off nt
	s_nop 1
	v_lshl_add_u64 v[68:69], v[66:67], 0, s[0:1]
	global_load_dwordx4 v[114:117], v[68:69], off nt
	v_readlane_b32 s0, v244, 40
	v_readlane_b32 s1, v244, 41
	s_nop 1
	v_lshl_add_u64 v[68:69], v[66:67], 0, s[0:1]
	v_readlane_b32 s0, v244, 42
	v_readlane_b32 s1, v244, 43
	global_load_dwordx4 v[118:121], v[68:69], off nt
	s_nop 1
	v_lshl_add_u64 v[68:69], v[66:67], 0, s[0:1]
	v_readlane_b32 s0, v244, 44
	v_readlane_b32 s1, v244, 45
	s_nop 1
	v_lshl_add_u64 v[70:71], v[66:67], 0, s[0:1]
	global_load_dwordx4 v[122:125], v[68:69], off nt
	global_load_dwordx4 v[126:129], v[70:71], off nt
	v_readlane_b32 s0, v244, 46
	v_readlane_b32 s1, v244, 47
	s_nop 1
	v_lshl_add_u64 v[68:69], v[66:67], 0, s[0:1]
	v_readlane_b32 s0, v244, 48
	v_readlane_b32 s1, v244, 49
	s_nop 1
	v_lshl_add_u64 v[70:71], v[66:67], 0, s[0:1]
	global_load_dwordx4 v[130:133], v[68:69], off nt
	global_load_dwordx4 v[134:137], v[70:71], off nt
	v_readlane_b32 s0, v244, 50
	v_readlane_b32 s1, v244, 51
	s_nop 1
	v_lshl_add_u64 v[68:69], v[66:67], 0, s[0:1]
	v_readlane_b32 s0, v244, 52
	v_readlane_b32 s1, v244, 53
	s_nop 1
	v_lshl_add_u64 v[70:71], v[66:67], 0, s[0:1]
	v_readlane_b32 s0, v244, 54
	v_readlane_b32 s1, v244, 55
	global_load_dwordx4 v[94:97], v[68:69], off nt
	global_load_dwordx4 v[90:93], v[70:71], off nt
	s_nop 1
	v_lshl_add_u64 v[68:69], v[66:67], 0, s[0:1]
	v_readlane_b32 s0, v244, 56
	v_readlane_b32 s1, v244, 57
	s_nop 1
	v_lshl_add_u64 v[70:71], v[66:67], 0, s[0:1]
	v_readlane_b32 s0, v244, 58
	v_readlane_b32 s1, v244, 59
	global_load_dwordx4 v[86:89], v[68:69], off nt
	global_load_dwordx4 v[82:85], v[70:71], off nt
	s_nop 1
	v_lshl_add_u64 v[68:69], v[66:67], 0, s[0:1]
	v_readlane_b32 s0, v244, 60
	v_readlane_b32 s1, v244, 61
	s_nop 1
	v_lshl_add_u64 v[70:71], v[66:67], 0, s[0:1]
	global_load_dwordx4 v[78:81], v[68:69], off nt
	global_load_dwordx4 v[74:77], v[70:71], off nt
	v_readlane_b32 s0, v244, 62
	v_readlane_b32 s1, v244, 63
	s_nop 1
	v_lshl_add_u64 v[68:69], v[66:67], 0, s[0:1]
	v_readlane_b32 s0, v243, 4
	v_readlane_b32 s1, v243, 5
	s_nop 1
	v_lshl_add_u64 v[66:67], v[66:67], 0, s[0:1]
	global_load_dwordx4 v[70:73], v[68:69], off nt
	global_load_dwordx4 v[66:69], v[66:67], off nt
	s_waitcnt vmcnt(15)
	v_pk_fma_f32 v[2:3], v[106:107], v[6:7], v[2:3] op_sel_hi:[1,0,1]
	v_pk_fma_f32 v[4:5], v[108:109], v[6:7], v[4:5] op_sel_hi:[1,0,1]
	v_sub_f32_e32 v6, v15, v104
	v_mul_f32_e32 v6, 0x3fb8aa3b, v6
	v_sub_f32_e32 v7, v16, v104
	v_exp_f32_e32 v6, v6
	v_mul_f32_e32 v7, 0x3fb8aa3b, v7
	v_exp_f32_e32 v7, v7
	v_mul_f32_e32 v6, v139, v6
	s_waitcnt vmcnt(14)
	v_pk_fma_f32 v[4:5], v[112:113], v[6:7], v[4:5] op_sel_hi:[1,0,1]
	v_pk_fma_f32 v[2:3], v[110:111], v[6:7], v[2:3] op_sel_hi:[1,0,1]
	v_mul_f32_e32 v6, v139, v7
	s_waitcnt vmcnt(13)
	v_pk_fma_f32 v[2:3], v[114:115], v[6:7], v[2:3] op_sel_hi:[1,0,1]
	v_pk_fma_f32 v[4:5], v[116:117], v[6:7], v[4:5] op_sel_hi:[1,0,1]
	v_sub_f32_e32 v6, v17, v104
	v_mul_f32_e32 v6, 0x3fb8aa3b, v6
	s_waitcnt lgkmcnt(0)
	v_sub_f32_e32 v7, v10, v104
	v_exp_f32_e32 v6, v6
	v_mul_f32_e32 v7, 0x3fb8aa3b, v7
	v_exp_f32_e32 v7, v7
	v_mul_f32_e32 v6, v139, v6
	s_waitcnt vmcnt(12)
	v_pk_fma_f32 v[4:5], v[120:121], v[6:7], v[4:5] op_sel_hi:[1,0,1]
	v_pk_fma_f32 v[2:3], v[118:119], v[6:7], v[2:3] op_sel_hi:[1,0,1]
	v_mul_f32_e32 v6, v139, v7
	s_waitcnt vmcnt(11)
	v_pk_fma_f32 v[2:3], v[122:123], v[6:7], v[2:3] op_sel_hi:[1,0,1]
	v_pk_fma_f32 v[4:5], v[124:125], v[6:7], v[4:5] op_sel_hi:[1,0,1]
	v_sub_f32_e32 v6, v11, v104
	v_mul_f32_e32 v6, 0x3fb8aa3b, v6
	v_sub_f32_e32 v7, v12, v104
	v_exp_f32_e32 v6, v6
	v_mul_f32_e32 v7, 0x3fb8aa3b, v7
	v_exp_f32_e32 v7, v7
	v_mul_f32_e32 v6, v139, v6
	s_waitcnt vmcnt(10)
	v_pk_fma_f32 v[4:5], v[128:129], v[6:7], v[4:5] op_sel_hi:[1,0,1]
	v_pk_fma_f32 v[2:3], v[126:127], v[6:7], v[2:3] op_sel_hi:[1,0,1]
	v_mul_f32_e32 v6, v139, v7
	v_sub_f32_e32 v7, v13, v104
	v_mul_f32_e32 v7, 0x3fb8aa3b, v7
	v_exp_f32_e32 v10, v7
	s_waitcnt vmcnt(9)
	v_pk_fma_f32 v[8:9], v[130:131], v[6:7], v[2:3] op_sel_hi:[1,0,1]
	v_pk_fma_f32 v[6:7], v[132:133], v[6:7], v[4:5] op_sel_hi:[1,0,1]
	ds_read_b128 v[2:5], v105 offset:96
	v_mul_f32_e32 v10, v139, v10
	s_waitcnt vmcnt(8)
	v_pk_fma_f32 v[12:13], v[136:137], v[10:11], v[6:7] op_sel_hi:[1,0,1]
	v_pk_fma_f32 v[10:11], v[134:135], v[10:11], v[8:9] op_sel_hi:[1,0,1]
	ds_read_b128 v[6:9], v105 offset:112
	s_waitcnt lgkmcnt(1)
	v_sub_f32_e32 v2, v2, v104
	v_mul_f32_e32 v2, 0x3fb8aa3b, v2
	v_sub_f32_e32 v3, v3, v104
	v_exp_f32_e32 v2, v2
	v_mul_f32_e32 v3, 0x3fb8aa3b, v3
	v_sub_f32_e32 v4, v4, v104
	v_exp_f32_e32 v14, v3
	v_mul_f32_e32 v4, 0x3fb8aa3b, v4
	v_sub_f32_e32 v5, v5, v104
	v_exp_f32_e32 v4, v4
	v_mul_f32_e32 v5, 0x3fb8aa3b, v5
	s_waitcnt lgkmcnt(0)
	v_sub_f32_e32 v6, v6, v104
	v_exp_f32_e32 v5, v5
	v_mul_f32_e32 v6, 0x3fb8aa3b, v6
	v_sub_f32_e32 v7, v7, v104
	v_mul_f32_e32 v2, v139, v2
	v_exp_f32_e32 v6, v6
	v_mul_f32_e32 v7, 0x3fb8aa3b, v7
	s_waitcnt vmcnt(7)
	v_pk_fma_f32 v[10:11], v[94:95], v[2:3], v[10:11] op_sel_hi:[1,0,1]
	v_pk_fma_f32 v[2:3], v[96:97], v[2:3], v[12:13] op_sel_hi:[1,0,1]
	v_mul_f32_e32 v12, v139, v14
	v_exp_f32_e32 v7, v7
	s_waitcnt vmcnt(6)
	v_pk_fma_f32 v[2:3], v[92:93], v[12:13], v[2:3] op_sel_hi:[1,0,1]
	v_pk_fma_f32 v[10:11], v[90:91], v[12:13], v[10:11] op_sel_hi:[1,0,1]
	v_mul_f32_e32 v4, v139, v4
	s_waitcnt vmcnt(5)
	v_pk_fma_f32 v[10:11], v[86:87], v[4:5], v[10:11] op_sel_hi:[1,0,1]
	v_pk_fma_f32 v[2:3], v[88:89], v[4:5], v[2:3] op_sel_hi:[1,0,1]
	v_mul_f32_e32 v4, v139, v5
	s_waitcnt vmcnt(4)
	v_pk_fma_f32 v[2:3], v[84:85], v[4:5], v[2:3] op_sel_hi:[1,0,1]
	v_pk_fma_f32 v[4:5], v[82:83], v[4:5], v[10:11] op_sel_hi:[1,0,1]
	v_mul_f32_e32 v6, v139, v6
	s_waitcnt vmcnt(3)
	v_pk_fma_f32 v[4:5], v[78:79], v[6:7], v[4:5] op_sel_hi:[1,0,1]
	v_pk_fma_f32 v[2:3], v[80:81], v[6:7], v[2:3] op_sel_hi:[1,0,1]
	v_mul_f32_e32 v6, v139, v7
	s_waitcnt vmcnt(2)
	v_pk_fma_f32 v[2:3], v[76:77], v[6:7], v[2:3] op_sel_hi:[1,0,1]
	v_pk_fma_f32 v[4:5], v[74:75], v[6:7], v[4:5] op_sel_hi:[1,0,1]
	v_sub_f32_e32 v6, v8, v104
	v_mul_f32_e32 v6, 0x3fb8aa3b, v6
	v_sub_f32_e32 v7, v9, v104
	v_exp_f32_e32 v6, v6
	v_mul_f32_e32 v7, 0x3fb8aa3b, v7
	v_exp_f32_e32 v7, v7
	v_mul_f32_e32 v6, v139, v6
	s_waitcnt vmcnt(1)
	v_pk_fma_f32 v[8:9], v[70:71], v[6:7], v[4:5] op_sel_hi:[1,0,1]
	v_pk_fma_f32 v[2:3], v[72:73], v[6:7], v[2:3] op_sel_hi:[1,0,1]
	v_mul_f32_e32 v6, v139, v7
	s_waitcnt vmcnt(0)
	v_pk_fma_f32 v[4:5], v[68:69], v[6:7], v[2:3] op_sel_hi:[1,0,1]
	v_pk_fma_f32 v[2:3], v[66:67], v[6:7], v[8:9] op_sel_hi:[1,0,1]
	ds_write_b128 v102, v[2:5] offset:4096
	s_waitcnt lgkmcnt(0)
	s_waitcnt lgkmcnt(0)
	s_barrier
	s_and_saveexec_b64 s[10:11], s[12:13]
	s_cbranch_execz .LBB11_2190
	ds_read2st64_b32 v[2:3], v103 offset0:16 offset1:20
	s_lshl_b64 s[0:1], s[88:89], 1
	s_add_u32 s0, s8, s0
	s_addc_u32 s1, s9, s1
	s_lshl_b32 s48, s68, 1
	s_waitcnt lgkmcnt(0)
	v_add_f32_e32 v2, 0, v2
	v_add_f32_e32 v4, v2, v3
	ds_read2st64_b32 v[2:3], v103 offset0:24 offset1:28
	s_add_u32 s0, s0, s48
	s_addc_u32 s1, s1, 0
	s_waitcnt lgkmcnt(0)
	v_add_f32_e32 v2, v4, v2
	v_add_f32_e32 v4, v2, v3
	ds_read2st64_b32 v[2:3], v103 offset0:32 offset1:36
	s_waitcnt lgkmcnt(0)
	v_add_f32_e32 v2, v4, v2
	v_add_f32_e32 v4, v2, v3
	ds_read2st64_b32 v[2:3], v103 offset0:40 offset1:44
	s_waitcnt lgkmcnt(0)
	v_add_f32_e32 v2, v4, v2
	v_add_f32_e32 v2, v2, v3
	v_cvt_pk_bf16_f32 v4, v2, v1
	v_lshl_add_u64 v[2:3], v[98:99], 1, s[0:1]
	global_store_short v[2:3], v4, off sc1
	s_branch .LBB11_2190
